# scan: next chunk's address math and global loads issued before the end-of-chunk workgroup barrier instead of after it (on top of the RES1 epilogue load batching)
# baseline (speedup 1.0000x reference)
;     ...
;   for (int ch = -1; ch < 72; ++ch) {
;     const int nx = ch + 1;
;     const bool more = nx < 72;
;     if (more) {
;       const int n0 = nx * 32; const bool cx = n0 < 256;
;       const int tlo = dir ? (cx ? 224 - n0 : 2528 - n0) : n0;
;       const int slo = cx ? 0 : 256, shi = cx ? 256 : 2304;
;       rg0 = *(const uint4*)(pb + (size_t)(tlo + (tid >> 5)) * INW);
;       rg1 = *(const uint4*)(pb + (size_t)(tlo + (tid >> 5) + 8) * INW);
;       rg2 = *(const uint4*)(pb + (size_t)(tlo + (tid >> 5) + 16) * INW);
;       rg3 = *(const uint4*)(pb + (size_t)(tlo + (tid >> 5) + 24) * INW);
;       rg4 = make_uint4(0, 0, 0, 0);
;       if (tid < 64) { const int tok = (tid >> 5) ? tlo + 32 : tlo - 1; if (tok >= slo && tok < shi) rg4 = *(const uint4*)(pb + (size_t)tok * INW); }
;     }
;     ...
;     __syncthreads();
.LBB0_350:
	v_add_u32_e32 v130, 32, v130
	v_subrev_u32_e32 v147, 32, v147
	s_mov_b32 s91, s90
	s_cmpk_lg_i32 s90, 0x48
	s_cbranch_scc1 .Lmy_hdr_pre
	s_waitcnt lgkmcnt(0)
	s_barrier
	s_branch .LBB0_386

;     ...
;     __syncthreads();
.Lmy_h357:
	s_waitcnt lgkmcnt(0)
	s_barrier
	s_branch .LBB0_357
